# MoBA pair loop: streamlined loop-tile instances (score block a then b; softmax of a in b's QK gaps, softmax of b in the first PV gaps; no mask branch / drain nop); own-block tiles keep the old instanc
# baseline (speedup 1.0000x reference)
.LBB0_74:
	s_cmp_eq_u64 s[36:37], 0
	s_cbranch_scc1 .Lmoba_a2
	v_add_u32_e32 v169, s9, v148
	v_add_u32_e32 v183, v169, v149
	v_add_u32_e32 v184, v169, v150
	v_add_u32_e32 v185, v169, v151
	v_add_u32_e32 v186, v169, v152
	ds_read_b128 v[170:173], v183
	ds_read_b128 v[174:177], v183 offset:8192
	ds_read_b128 v[178:181], v184
	ds_read_b128 v[188:191], v184 offset:8192
	ds_read_b128 v[192:195], v185
	ds_read_b128 v[198:201], v185 offset:8192
	ds_read_b128 v[202:205], v186
	s_add_i32 s10, s6, 0x80
	v_cmp_gt_i32_e32 vcc, s10, v167
	s_and_b64 s[10:11], s[36:37], vcc
	v_cmp_lt_i32_e64 s[40:41], -1, v140
	v_xor_b32_e32 v223, 0x80000000, v142
	s_nop 0
	v_cndmask_b32_e64 v222, v235, v223, s[40:41]
	v_cndmask_b32_e64 v222, v222, v223, s[36:37]
	v_mov_b32_e32 v206, v222
	v_mov_b32_e32 v207, v222
	v_mov_b32_e32 v208, v222
	v_mov_b32_e32 v209, v222
	v_mov_b32_e32 v210, v222
	v_mov_b32_e32 v211, v222
	v_mov_b32_e32 v212, v222
	v_mov_b32_e32 v213, v222
	v_mov_b32_e32 v214, v222
	v_mov_b32_e32 v215, v222
	v_mov_b32_e32 v216, v222
	v_mov_b32_e32 v217, v222
	v_mov_b32_e32 v218, v222
	v_mov_b32_e32 v219, v222
	v_mov_b32_e32 v220, v222
	v_mov_b32_e32 v221, v222
	v_add_u32_e32 v187, v169, v153
	v_add_u32_e32 v222, v169, v154
	v_add_u32_e32 v223, v169, v155
	v_add_u32_e32 v169, v169, v156
	s_waitcnt lgkmcnt(6)
	v_mfma_f32_32x32x16_bf16 v[80:95], v[170:173], v[98:101], v[206:221]
	ds_read_b128 v[170:173], v186 offset:8192
	v_add_u32_e32 v96, s9, v159
	v_add3_u32 v96, v96, v160, v157
	v_add_u32_e32 v132, v96, v161
	v_add_u32_e32 v134, v96, v162
	v_add_u32_e32 v135, v96, v163
	v_add_u32_e32 v96, v96, v158
	s_waitcnt lgkmcnt(6)
	v_mfma_f32_32x32x16_bf16 v[64:79], v[174:177], v[98:101], v[206:221]
	ds_read_b128 v[174:177], v187
	s_waitcnt lgkmcnt(6)
	v_mfma_f32_32x32x16_bf16 v[80:95], v[178:181], v[102:105], v[80:95]
	ds_read_b128 v[178:181], v187 offset:8192
	s_waitcnt lgkmcnt(6)
	v_mfma_f32_32x32x16_bf16 v[64:79], v[188:191], v[102:105], v[64:79]
	ds_read_b128 v[188:191], v222
	s_waitcnt lgkmcnt(6)
	v_mfma_f32_32x32x16_bf16 v[80:95], v[192:195], v[106:109], v[80:95]
	ds_read_b128 v[192:195], v222 offset:8192
	s_waitcnt lgkmcnt(6)
	v_mfma_f32_32x32x16_bf16 v[64:79], v[198:201], v[106:109], v[64:79]
	ds_read_b128 v[198:201], v223
	s_waitcnt lgkmcnt(6)
	v_mfma_f32_32x32x16_bf16 v[80:95], v[202:205], v[110:113], v[80:95]
	ds_read_b128 v[202:205], v223 offset:8192
	s_waitcnt lgkmcnt(6)
	v_mfma_f32_32x32x16_bf16 v[64:79], v[170:173], v[110:113], v[64:79]
	ds_read_b128 v[170:173], v169
	s_waitcnt lgkmcnt(6)
	v_mfma_f32_32x32x16_bf16 v[80:95], v[174:177], v[114:117], v[80:95]
	ds_read_b128 v[174:177], v169 offset:8192
	s_waitcnt lgkmcnt(6)
	v_mfma_f32_32x32x16_bf16 v[64:79], v[178:181], v[114:117], v[64:79]
	s_waitcnt lgkmcnt(5)
	v_mfma_f32_32x32x16_bf16 v[80:95], v[188:191], v[118:121], v[80:95]
	ds_read_b64_tr_b16 v[188:189], v96 offset:16384
	ds_read_b64_tr_b16 v[190:191], v96 offset:18432
	s_waitcnt lgkmcnt(6)
	v_mfma_f32_32x32x16_bf16 v[64:79], v[192:195], v[118:121], v[64:79]
	ds_read_b64_tr_b16 v[192:193], v132 offset:16384
	ds_read_b64_tr_b16 v[194:195], v132 offset:18432
	s_waitcnt lgkmcnt(7)
	v_mfma_f32_32x32x16_bf16 v[80:95], v[198:201], v[122:125], v[80:95]
	ds_read_b64_tr_b16 v[198:199], v134 offset:16384
	ds_read_b64_tr_b16 v[200:201], v134 offset:18432
	s_waitcnt lgkmcnt(8)
	v_mfma_f32_32x32x16_bf16 v[64:79], v[202:205], v[122:125], v[64:79]
	ds_read_b64_tr_b16 v[202:203], v135 offset:16384
	ds_read_b64_tr_b16 v[204:205], v135 offset:18432
	s_waitcnt lgkmcnt(9)
	v_mfma_f32_32x32x16_bf16 v[80:95], v[170:173], v[126:129], v[80:95]
	s_waitcnt lgkmcnt(8)
	v_mfma_f32_32x32x16_bf16 v[64:79], v[174:177], v[126:129], v[64:79]
	s_and_saveexec_b64 s[40:41], s[10:11]
	s_cbranch_execz .LBB0_76
	v_sub_u32_e32 v169, v140, v146
	v_cmp_lt_i32_e32 vcc, -1, v169
	s_nop 4
	v_cndmask_b32_e32 v80, v235, v80, vcc
	v_cmp_lt_i32_e32 vcc, 0, v169
	s_nop 1
	v_cndmask_b32_e32 v81, v235, v81, vcc
	v_cmp_lt_i32_e32 vcc, 1, v169
	s_nop 1
	v_cndmask_b32_e32 v82, v235, v82, vcc
	v_cmp_lt_i32_e32 vcc, 2, v169
	s_nop 1
	v_cndmask_b32_e32 v83, v235, v83, vcc
	v_cmp_lt_i32_e32 vcc, 7, v169
	s_nop 1
	v_cndmask_b32_e32 v84, v235, v84, vcc
	v_cmp_lt_i32_e32 vcc, 8, v169
	s_nop 1
	v_cndmask_b32_e32 v85, v235, v85, vcc
	v_cmp_lt_i32_e32 vcc, 9, v169
	s_nop 1
	v_cndmask_b32_e32 v86, v235, v86, vcc
	v_cmp_lt_i32_e32 vcc, 10, v169
	s_nop 1
	v_cndmask_b32_e32 v87, v235, v87, vcc
	v_cmp_lt_i32_e32 vcc, 15, v169
	s_nop 1
	v_cndmask_b32_e32 v88, v235, v88, vcc
	v_cmp_lt_i32_e32 vcc, 16, v169
	s_nop 1
	v_cndmask_b32_e32 v89, v235, v89, vcc
	v_cmp_lt_i32_e32 vcc, 17, v169
	s_nop 1
	v_cndmask_b32_e32 v90, v235, v90, vcc
	v_cmp_lt_i32_e32 vcc, 18, v169
	s_nop 1
	v_cndmask_b32_e32 v91, v235, v91, vcc
	v_cmp_lt_i32_e32 vcc, 23, v169
	s_nop 1
	v_cndmask_b32_e32 v92, v235, v92, vcc
	v_cmp_lt_i32_e32 vcc, 24, v169
	s_nop 1
	v_cndmask_b32_e32 v93, v235, v93, vcc
	v_cmp_lt_i32_e32 vcc, 25, v169
	s_nop 1
	v_cndmask_b32_e32 v94, v235, v94, vcc
	v_cmp_lt_i32_e32 vcc, 26, v169
	s_nop 1
	v_cndmask_b32_e32 v95, v235, v95, vcc
	v_cmp_lt_i32_e32 vcc, 31, v169
	s_nop 1
	v_cndmask_b32_e32 v64, v235, v64, vcc
	v_cmp_lt_i32_e32 vcc, 32, v169
	s_nop 1
	v_cndmask_b32_e32 v65, v235, v65, vcc
	v_cmp_lt_i32_e32 vcc, 33, v169
	s_nop 1
	v_cndmask_b32_e32 v66, v235, v66, vcc
	v_cmp_lt_i32_e32 vcc, 34, v169
	s_nop 1
	v_cndmask_b32_e32 v67, v235, v67, vcc
	v_cmp_lt_i32_e32 vcc, 39, v169
	s_nop 1
	v_cndmask_b32_e32 v68, v235, v68, vcc
	v_cmp_lt_i32_e32 vcc, 40, v169
	s_nop 1
	v_cndmask_b32_e32 v69, v235, v69, vcc
	v_cmp_lt_i32_e32 vcc, 41, v169
	s_nop 1
	v_cndmask_b32_e32 v70, v235, v70, vcc
	v_cmp_lt_i32_e32 vcc, 42, v169
	s_nop 1
	v_cndmask_b32_e32 v71, v235, v71, vcc
	v_cmp_lt_i32_e32 vcc, 47, v169
	s_nop 1
	v_cndmask_b32_e32 v72, v235, v72, vcc
	v_cmp_lt_i32_e32 vcc, 48, v169
	s_nop 1
	v_cndmask_b32_e32 v73, v235, v73, vcc
	v_cmp_lt_i32_e32 vcc, 49, v169
	s_nop 1
	v_cndmask_b32_e32 v74, v235, v74, vcc
	v_cmp_lt_i32_e32 vcc, 50, v169
	s_nop 1
	v_cndmask_b32_e32 v75, v235, v75, vcc
	v_cmp_lt_i32_e32 vcc, 55, v169
	s_nop 1
	v_cndmask_b32_e32 v76, v235, v76, vcc
	v_cmp_lt_i32_e32 vcc, 56, v169
	s_nop 1
	v_cndmask_b32_e32 v77, v235, v77, vcc
	v_cmp_lt_i32_e32 vcc, 57, v169
	s_nop 1
	v_cndmask_b32_e32 v78, v235, v78, vcc
	v_cmp_lt_i32_e32 vcc, 58, v169
	s_nop 1
	v_cndmask_b32_e32 v79, v235, v79, vcc

.LBB0_84:
	s_cmp_eq_u64 s[36:37], 0
	s_cbranch_scc1 .Lmoba_b2
	ds_read_b128 v[170:173], v183 offset:32768
	ds_read_b128 v[174:177], v183 offset:40960
	ds_read_b128 v[178:181], v184 offset:32768
	ds_read_b128 v[188:191], v184 offset:40960
	ds_read_b128 v[192:195], v185 offset:32768
	ds_read_b128 v[198:201], v185 offset:40960
	ds_read_b128 v[202:205], v186 offset:32768
	s_add_i32 s10, s6, 0xc0
	v_cmp_gt_i32_e32 vcc, s10, v167
	s_and_b64 s[10:11], s[36:37], vcc
	s_waitcnt lgkmcnt(6)
	v_mfma_f32_32x32x16_bf16 v[80:95], v[170:173], v[98:101], v[206:221]
	ds_read_b128 v[170:173], v186 offset:40960
	s_waitcnt lgkmcnt(6)
	v_mfma_f32_32x32x16_bf16 v[64:79], v[174:177], v[98:101], v[206:221]
	ds_read_b128 v[174:177], v187 offset:32768
	s_waitcnt lgkmcnt(6)
	v_mfma_f32_32x32x16_bf16 v[80:95], v[178:181], v[102:105], v[80:95]
	ds_read_b128 v[178:181], v187 offset:40960
	s_waitcnt lgkmcnt(6)
	v_mfma_f32_32x32x16_bf16 v[64:79], v[188:191], v[102:105], v[64:79]
	ds_read_b128 v[188:191], v222 offset:32768
	s_waitcnt lgkmcnt(6)
	v_mfma_f32_32x32x16_bf16 v[80:95], v[192:195], v[106:109], v[80:95]
	ds_read_b128 v[192:195], v222 offset:40960
	s_waitcnt lgkmcnt(6)
	v_mfma_f32_32x32x16_bf16 v[64:79], v[198:201], v[106:109], v[64:79]
	ds_read_b128 v[198:201], v223 offset:32768
	s_waitcnt lgkmcnt(6)
	v_mfma_f32_32x32x16_bf16 v[80:95], v[202:205], v[110:113], v[80:95]
	ds_read_b128 v[202:205], v223 offset:40960
	s_waitcnt lgkmcnt(6)
	v_mfma_f32_32x32x16_bf16 v[64:79], v[170:173], v[110:113], v[64:79]
	ds_read_b128 v[170:173], v169 offset:32768
	s_waitcnt lgkmcnt(6)
	v_mfma_f32_32x32x16_bf16 v[80:95], v[174:177], v[114:117], v[80:95]
	ds_read_b128 v[174:177], v169 offset:40960
	s_waitcnt lgkmcnt(6)
	v_mfma_f32_32x32x16_bf16 v[64:79], v[178:181], v[114:117], v[64:79]
	s_waitcnt lgkmcnt(5)
	v_mfma_f32_32x32x16_bf16 v[80:95], v[188:191], v[118:121], v[80:95]
	ds_read_b64_tr_b16 v[188:189], v96 offset:49152
	ds_read_b64_tr_b16 v[190:191], v96 offset:51200
	s_waitcnt lgkmcnt(6)
	v_mfma_f32_32x32x16_bf16 v[64:79], v[192:195], v[118:121], v[64:79]
	ds_read_b64_tr_b16 v[192:193], v132 offset:49152
	ds_read_b64_tr_b16 v[194:195], v132 offset:51200
	s_waitcnt lgkmcnt(7)
	v_mfma_f32_32x32x16_bf16 v[80:95], v[198:201], v[122:125], v[80:95]
	ds_read_b64_tr_b16 v[198:199], v134 offset:49152
	ds_read_b64_tr_b16 v[200:201], v134 offset:51200
	s_waitcnt lgkmcnt(8)
	v_mfma_f32_32x32x16_bf16 v[64:79], v[202:205], v[122:125], v[64:79]
	ds_read_b64_tr_b16 v[202:203], v135 offset:49152
	ds_read_b64_tr_b16 v[204:205], v135 offset:51200
	s_waitcnt lgkmcnt(9)
	v_mfma_f32_32x32x16_bf16 v[80:95], v[170:173], v[126:129], v[80:95]
	s_waitcnt lgkmcnt(8)
	v_mfma_f32_32x32x16_bf16 v[64:79], v[174:177], v[126:129], v[64:79]
	s_and_saveexec_b64 s[38:39], s[10:11]
	s_cbranch_execz .LBB0_86
	v_sub_u32_e32 v140, v133, v146
	v_cmp_lt_i32_e32 vcc, -1, v140
	s_nop 4
	v_cndmask_b32_e32 v80, v235, v80, vcc
	v_cmp_lt_i32_e32 vcc, 0, v140
	s_nop 1
	v_cndmask_b32_e32 v81, v235, v81, vcc
	v_cmp_lt_i32_e32 vcc, 1, v140
	s_nop 1
	v_cndmask_b32_e32 v82, v235, v82, vcc
	v_cmp_lt_i32_e32 vcc, 2, v140
	s_nop 1
	v_cndmask_b32_e32 v83, v235, v83, vcc
	v_cmp_lt_i32_e32 vcc, 7, v140
	s_nop 1
	v_cndmask_b32_e32 v84, v235, v84, vcc
	v_cmp_lt_i32_e32 vcc, 8, v140
	s_nop 1
	v_cndmask_b32_e32 v85, v235, v85, vcc
	v_cmp_lt_i32_e32 vcc, 9, v140
	s_nop 1
	v_cndmask_b32_e32 v86, v235, v86, vcc
	v_cmp_lt_i32_e32 vcc, 10, v140
	s_nop 1
	v_cndmask_b32_e32 v87, v235, v87, vcc
	v_cmp_lt_i32_e32 vcc, 15, v140
	s_nop 1
	v_cndmask_b32_e32 v88, v235, v88, vcc
	v_cmp_lt_i32_e32 vcc, 16, v140
	s_nop 1
	v_cndmask_b32_e32 v89, v235, v89, vcc
	v_cmp_lt_i32_e32 vcc, 17, v140
	s_nop 1
	v_cndmask_b32_e32 v90, v235, v90, vcc
	v_cmp_lt_i32_e32 vcc, 18, v140
	s_nop 1
	v_cndmask_b32_e32 v91, v235, v91, vcc
	v_cmp_lt_i32_e32 vcc, 23, v140
	s_nop 1
	v_cndmask_b32_e32 v92, v235, v92, vcc
	v_cmp_lt_i32_e32 vcc, 24, v140
	s_nop 1
	v_cndmask_b32_e32 v93, v235, v93, vcc
	v_cmp_lt_i32_e32 vcc, 25, v140
	s_nop 1
	v_cndmask_b32_e32 v94, v235, v94, vcc
	v_cmp_lt_i32_e32 vcc, 26, v140
	s_nop 1
	v_cndmask_b32_e32 v95, v235, v95, vcc
	v_cmp_lt_i32_e32 vcc, 31, v140
	s_nop 1
	v_cndmask_b32_e32 v64, v235, v64, vcc
	v_cmp_lt_i32_e32 vcc, 32, v140
	s_nop 1
	v_cndmask_b32_e32 v65, v235, v65, vcc
	v_cmp_lt_i32_e32 vcc, 33, v140
	s_nop 1
	v_cndmask_b32_e32 v66, v235, v66, vcc
	v_cmp_lt_i32_e32 vcc, 34, v140
	s_nop 1
	v_cndmask_b32_e32 v67, v235, v67, vcc
	v_cmp_lt_i32_e32 vcc, 39, v140
	s_nop 1
	v_cndmask_b32_e32 v68, v235, v68, vcc
	v_cmp_lt_i32_e32 vcc, 40, v140
	s_nop 1
	v_cndmask_b32_e32 v69, v235, v69, vcc
	v_cmp_lt_i32_e32 vcc, 41, v140
	s_nop 1
	v_cndmask_b32_e32 v70, v235, v70, vcc
	v_cmp_lt_i32_e32 vcc, 42, v140
	s_nop 1
	v_cndmask_b32_e32 v71, v235, v71, vcc
	v_cmp_lt_i32_e32 vcc, 47, v140
	s_nop 1
	v_cndmask_b32_e32 v72, v235, v72, vcc
	v_cmp_lt_i32_e32 vcc, 48, v140
	s_nop 1
	v_cndmask_b32_e32 v73, v235, v73, vcc
	v_cmp_lt_i32_e32 vcc, 49, v140
	s_nop 1
	v_cndmask_b32_e32 v74, v235, v74, vcc
	v_cmp_lt_i32_e32 vcc, 50, v140
	s_nop 1
	v_cndmask_b32_e32 v75, v235, v75, vcc
	v_cmp_lt_i32_e32 vcc, 55, v140
	s_nop 1
	v_cndmask_b32_e32 v76, v235, v76, vcc
	v_cmp_lt_i32_e32 vcc, 56, v140
	s_nop 1
	v_cndmask_b32_e32 v77, v235, v77, vcc
	v_cmp_lt_i32_e32 vcc, 57, v140
	s_nop 1
	v_cndmask_b32_e32 v78, v235, v78, vcc
	v_cmp_lt_i32_e32 vcc, 58, v140
	s_nop 1
	v_cndmask_b32_e32 v79, v235, v79, vcc

.Lmoba_a2:
	v_add_u32_e32 v169, s9, v148
	v_add_u32_e32 v183, v169, v149
	v_add_u32_e32 v184, v169, v150
	v_add_u32_e32 v185, v169, v151
	v_add_u32_e32 v186, v169, v152
	v_add_u32_e32 v187, v169, v153
	ds_read_b128 v[170:173], v183
	ds_read_b128 v[174:177], v184
	ds_read_b128 v[178:181], v185
	ds_read_b128 v[188:191], v186
	ds_read_b128 v[192:195], v187
	v_cmp_lt_i32_e64 s[40:41], -1, v140
	v_xor_b32_e32 v223, 0x80000000, v142
	s_nop 0
	v_cndmask_b32_e64 v222, v235, v223, s[40:41]
	v_mov_b32_e32 v206, v222
	v_mov_b32_e32 v207, v222
	v_mov_b32_e32 v208, v222
	v_mov_b32_e32 v209, v222
	v_mov_b32_e32 v210, v222
	v_mov_b32_e32 v211, v222
	v_mov_b32_e32 v212, v222
	v_mov_b32_e32 v213, v222
	v_mov_b32_e32 v214, v222
	v_mov_b32_e32 v215, v222
	v_mov_b32_e32 v216, v222
	v_mov_b32_e32 v217, v222
	v_mov_b32_e32 v218, v222
	v_mov_b32_e32 v219, v222
	v_mov_b32_e32 v220, v222
	v_mov_b32_e32 v221, v222
	v_add_u32_e32 v222, v169, v154
	v_add_u32_e32 v223, v169, v155
	v_add_u32_e32 v169, v169, v156
	ds_read_b128 v[198:201], v222
	ds_read_b128 v[202:205], v223
	s_waitcnt lgkmcnt(6)
	v_mfma_f32_32x32x16_bf16 v[80:95], v[170:173], v[98:101], v[206:221]
	ds_read_b128 v[170:173], v169
	v_add_u32_e32 v96, s9, v159
	v_add3_u32 v96, v96, v160, v157
	s_waitcnt lgkmcnt(6)
	v_mfma_f32_32x32x16_bf16 v[80:95], v[174:177], v[102:105], v[80:95]
	ds_read_b128 v[174:177], v183 offset:8192
	v_add_u32_e32 v132, v96, v161
	v_add_u32_e32 v134, v96, v162
	s_waitcnt lgkmcnt(6)
	v_mfma_f32_32x32x16_bf16 v[80:95], v[178:181], v[106:109], v[80:95]
	ds_read_b128 v[178:181], v184 offset:8192
	v_add_u32_e32 v135, v96, v163
	s_waitcnt lgkmcnt(6)
	v_mfma_f32_32x32x16_bf16 v[80:95], v[188:191], v[110:113], v[80:95]
	ds_read_b128 v[188:191], v185 offset:8192
	v_add_u32_e32 v96, v96, v158
	s_waitcnt lgkmcnt(6)
	v_mfma_f32_32x32x16_bf16 v[80:95], v[192:195], v[114:117], v[80:95]
	ds_read_b128 v[192:195], v186 offset:8192
	s_waitcnt lgkmcnt(6)
	v_mfma_f32_32x32x16_bf16 v[80:95], v[198:201], v[118:121], v[80:95]
	ds_read_b128 v[198:201], v187 offset:8192
	s_waitcnt lgkmcnt(6)
	v_mfma_f32_32x32x16_bf16 v[80:95], v[202:205], v[122:125], v[80:95]
	ds_read_b128 v[202:205], v222 offset:8192
	s_waitcnt lgkmcnt(6)
	v_mfma_f32_32x32x16_bf16 v[80:95], v[170:173], v[126:129], v[80:95]
	ds_read_b128 v[170:173], v223 offset:8192
	s_waitcnt lgkmcnt(6)
	v_mfma_f32_32x32x16_bf16 v[64:79], v[174:177], v[98:101], v[206:221]
	ds_read_b128 v[174:177], v169 offset:8192
	s_nop 7
	v_exp_f32_e32 v80, v80
	v_exp_f32_e32 v81, v81
	v_add_f32_e32 v168, v168, v80
	v_add_f32_e32 v168, v168, v81
	v_cvt_pk_bf16_f32 v80, v80, v81
	s_waitcnt lgkmcnt(6)
	v_mfma_f32_32x32x16_bf16 v[64:79], v[178:181], v[102:105], v[64:79]
	ds_read_b64_tr_b16 v[178:179], v96 offset:16384
	ds_read_b64_tr_b16 v[180:181], v96 offset:18432
	v_exp_f32_e32 v82, v82
	v_exp_f32_e32 v83, v83
	v_add_f32_e32 v168, v168, v82
	v_add_f32_e32 v168, v168, v83
	v_cvt_pk_bf16_f32 v81, v82, v83
	s_waitcnt lgkmcnt(7)
	v_mfma_f32_32x32x16_bf16 v[64:79], v[188:191], v[106:109], v[64:79]
	ds_read_b64_tr_b16 v[188:189], v132 offset:16384
	ds_read_b64_tr_b16 v[190:191], v132 offset:18432
	v_exp_f32_e32 v84, v84
	v_exp_f32_e32 v85, v85
	v_add_f32_e32 v168, v168, v84
	v_add_f32_e32 v168, v168, v85
	v_cvt_pk_bf16_f32 v82, v84, v85
	s_waitcnt lgkmcnt(8)
	v_mfma_f32_32x32x16_bf16 v[64:79], v[192:195], v[110:113], v[64:79]
	ds_read_b64_tr_b16 v[192:193], v134 offset:16384
	ds_read_b64_tr_b16 v[194:195], v134 offset:18432
	v_exp_f32_e32 v86, v86
	v_exp_f32_e32 v87, v87
	v_add_f32_e32 v168, v168, v86
	v_add_f32_e32 v168, v168, v87
	v_cvt_pk_bf16_f32 v83, v86, v87
	s_waitcnt lgkmcnt(9)
	v_mfma_f32_32x32x16_bf16 v[64:79], v[198:201], v[114:117], v[64:79]
	ds_read_b64_tr_b16 v[198:199], v135 offset:16384
	ds_read_b64_tr_b16 v[200:201], v135 offset:18432
	v_exp_f32_e32 v88, v88
	v_exp_f32_e32 v89, v89
	v_add_f32_e32 v168, v168, v88
	v_add_f32_e32 v168, v168, v89
	v_cvt_pk_bf16_f32 v84, v88, v89
	s_waitcnt lgkmcnt(10)
	v_mfma_f32_32x32x16_bf16 v[64:79], v[202:205], v[118:121], v[64:79]
	ds_read_b64_tr_b16 v[202:203], v96 offset:20480
	ds_read_b64_tr_b16 v[204:205], v96 offset:22528
	v_exp_f32_e32 v90, v90
	v_exp_f32_e32 v91, v91
	v_add_f32_e32 v168, v168, v90
	v_add_f32_e32 v168, v168, v91
	v_cvt_pk_bf16_f32 v85, v90, v91
	s_waitcnt lgkmcnt(11)
	v_mfma_f32_32x32x16_bf16 v[64:79], v[170:173], v[122:125], v[64:79]
	ds_read_b64_tr_b16 v[170:171], v132 offset:20480
	ds_read_b64_tr_b16 v[172:173], v132 offset:22528
	v_exp_f32_e32 v92, v92
	v_exp_f32_e32 v93, v93
	v_add_f32_e32 v168, v168, v92
	v_add_f32_e32 v168, v168, v93
	v_cvt_pk_bf16_f32 v86, v92, v93
	s_waitcnt lgkmcnt(12)
	v_mfma_f32_32x32x16_bf16 v[64:79], v[174:177], v[126:129], v[64:79]
	ds_read_b64_tr_b16 v[174:175], v134 offset:20480
	ds_read_b64_tr_b16 v[176:177], v134 offset:22528
	v_exp_f32_e32 v94, v94
	v_exp_f32_e32 v95, v95
	v_add_f32_e32 v168, v168, v94
	v_add_f32_e32 v168, v168, v95
	v_cvt_pk_bf16_f32 v87, v94, v95
	s_waitcnt lgkmcnt(12)
	v_mfma_f32_32x32x16_bf16 v[48:63], v[178:181], v[80:83], v[48:63]
	ds_read_b64_tr_b16 v[178:179], v135 offset:20480
	ds_read_b64_tr_b16 v[180:181], v135 offset:22528
	s_waitcnt lgkmcnt(12)
	v_mfma_f32_32x32x16_bf16 v[32:47], v[188:191], v[80:83], v[32:47]
	ds_read_b64_tr_b16 v[188:189], v96 offset:24576
	ds_read_b64_tr_b16 v[190:191], v96 offset:26624
	s_waitcnt lgkmcnt(12)
	v_mfma_f32_32x32x16_bf16 v[16:31], v[192:195], v[80:83], v[16:31]
	ds_read_b64_tr_b16 v[192:193], v132 offset:24576
	ds_read_b64_tr_b16 v[194:195], v132 offset:26624
	v_exp_f32_e32 v64, v64
	v_exp_f32_e32 v65, v65
	v_add_f32_e32 v168, v168, v64
	v_add_f32_e32 v168, v168, v65
	v_cvt_pk_bf16_f32 v88, v64, v65
	s_waitcnt lgkmcnt(12)
	v_mfma_f32_32x32x16_bf16 v[0:15], v[198:201], v[80:83], v[0:15]
	ds_read_b64_tr_b16 v[198:199], v134 offset:24576
	ds_read_b64_tr_b16 v[200:201], v134 offset:26624
	v_exp_f32_e32 v66, v66
	v_exp_f32_e32 v67, v67
	v_add_f32_e32 v168, v168, v66
	v_add_f32_e32 v168, v168, v67
	v_cvt_pk_bf16_f32 v89, v66, v67
	s_waitcnt lgkmcnt(12)
	v_mfma_f32_32x32x16_bf16 v[48:63], v[202:205], v[84:87], v[48:63]
	ds_read_b64_tr_b16 v[202:203], v135 offset:24576
	ds_read_b64_tr_b16 v[204:205], v135 offset:26624
	v_exp_f32_e32 v68, v68
	v_exp_f32_e32 v69, v69
	v_add_f32_e32 v168, v168, v68
	v_add_f32_e32 v168, v168, v69
	v_cvt_pk_bf16_f32 v90, v68, v69
	s_waitcnt lgkmcnt(12)
	v_mfma_f32_32x32x16_bf16 v[32:47], v[170:173], v[84:87], v[32:47]
	ds_read_b64_tr_b16 v[170:171], v96 offset:28672
	ds_read_b64_tr_b16 v[172:173], v96 offset:30720
	v_exp_f32_e32 v70, v70
	v_exp_f32_e32 v71, v71
	v_add_f32_e32 v168, v168, v70
	v_add_f32_e32 v168, v168, v71
	v_cvt_pk_bf16_f32 v91, v70, v71
	s_waitcnt lgkmcnt(12)
	v_mfma_f32_32x32x16_bf16 v[16:31], v[174:177], v[84:87], v[16:31]
	ds_read_b64_tr_b16 v[174:175], v132 offset:28672
	ds_read_b64_tr_b16 v[176:177], v132 offset:30720
	s_waitcnt lgkmcnt(12)
	v_mfma_f32_32x32x16_bf16 v[0:15], v[178:181], v[84:87], v[0:15]
	ds_read_b64_tr_b16 v[178:179], v134 offset:28672
	ds_read_b64_tr_b16 v[180:181], v134 offset:30720
	v_exp_f32_e32 v72, v72
	v_exp_f32_e32 v73, v73
	v_add_f32_e32 v168, v168, v72
	v_add_f32_e32 v168, v168, v73
	v_cvt_pk_bf16_f32 v92, v72, v73
	s_waitcnt lgkmcnt(12)
	v_mfma_f32_32x32x16_bf16 v[48:63], v[188:191], v[88:91], v[48:63]
	ds_read_b64_tr_b16 v[188:189], v135 offset:28672
	ds_read_b64_tr_b16 v[190:191], v135 offset:30720
	v_exp_f32_e32 v74, v74
	v_exp_f32_e32 v75, v75
	v_add_f32_e32 v168, v168, v74
	v_add_f32_e32 v168, v168, v75
	v_cvt_pk_bf16_f32 v93, v74, v75
	s_waitcnt lgkmcnt(12)
	v_mfma_f32_32x32x16_bf16 v[32:47], v[192:195], v[88:91], v[32:47]
	v_exp_f32_e32 v76, v76
	v_exp_f32_e32 v77, v77
	v_add_f32_e32 v168, v168, v76
	v_add_f32_e32 v168, v168, v77
	v_cvt_pk_bf16_f32 v94, v76, v77
	s_waitcnt lgkmcnt(10)
	v_mfma_f32_32x32x16_bf16 v[16:31], v[198:201], v[88:91], v[16:31]
	v_exp_f32_e32 v78, v78
	v_exp_f32_e32 v79, v79
	v_add_f32_e32 v168, v168, v78
	v_add_f32_e32 v168, v168, v79
	v_cvt_pk_bf16_f32 v95, v78, v79
	s_waitcnt lgkmcnt(8)
	v_mfma_f32_32x32x16_bf16 v[0:15], v[202:205], v[88:91], v[0:15]
	s_waitcnt lgkmcnt(6)
	v_mfma_f32_32x32x16_bf16 v[48:63], v[170:173], v[92:95], v[48:63]
	s_waitcnt lgkmcnt(4)
	v_mfma_f32_32x32x16_bf16 v[32:47], v[174:177], v[92:95], v[32:47]
	s_waitcnt lgkmcnt(2)
	v_mfma_f32_32x32x16_bf16 v[16:31], v[178:181], v[92:95], v[16:31]
	s_waitcnt lgkmcnt(0)
	v_mfma_f32_32x32x16_bf16 v[0:15], v[188:191], v[92:95], v[0:15]
	s_branch .LBB0_79
.Lmoba_b2:
	ds_read_b128 v[170:173], v183 offset:32768
	ds_read_b128 v[174:177], v184 offset:32768
	ds_read_b128 v[178:181], v185 offset:32768
	ds_read_b128 v[188:191], v186 offset:32768
	ds_read_b128 v[192:195], v187 offset:32768
	ds_read_b128 v[198:201], v222 offset:32768
	ds_read_b128 v[202:205], v223 offset:32768
	s_waitcnt lgkmcnt(6)
	v_mfma_f32_32x32x16_bf16 v[80:95], v[170:173], v[98:101], v[206:221]
	ds_read_b128 v[170:173], v169 offset:32768
	s_waitcnt lgkmcnt(6)
	v_mfma_f32_32x32x16_bf16 v[80:95], v[174:177], v[102:105], v[80:95]
	ds_read_b128 v[174:177], v183 offset:40960
	s_waitcnt lgkmcnt(6)
	v_mfma_f32_32x32x16_bf16 v[80:95], v[178:181], v[106:109], v[80:95]
	ds_read_b128 v[178:181], v184 offset:40960
	s_waitcnt lgkmcnt(6)
	v_mfma_f32_32x32x16_bf16 v[80:95], v[188:191], v[110:113], v[80:95]
	ds_read_b128 v[188:191], v185 offset:40960
	s_waitcnt lgkmcnt(6)
	v_mfma_f32_32x32x16_bf16 v[80:95], v[192:195], v[114:117], v[80:95]
	ds_read_b128 v[192:195], v186 offset:40960
	s_waitcnt lgkmcnt(6)
	v_mfma_f32_32x32x16_bf16 v[80:95], v[198:201], v[118:121], v[80:95]
	ds_read_b128 v[198:201], v187 offset:40960
	s_waitcnt lgkmcnt(6)
	v_mfma_f32_32x32x16_bf16 v[80:95], v[202:205], v[122:125], v[80:95]
	ds_read_b128 v[202:205], v222 offset:40960
	s_waitcnt lgkmcnt(6)
	v_mfma_f32_32x32x16_bf16 v[80:95], v[170:173], v[126:129], v[80:95]
	ds_read_b128 v[170:173], v223 offset:40960
	s_waitcnt lgkmcnt(6)
	v_mfma_f32_32x32x16_bf16 v[64:79], v[174:177], v[98:101], v[206:221]
	ds_read_b128 v[174:177], v169 offset:40960
	s_nop 7
	v_exp_f32_e32 v80, v80
	v_exp_f32_e32 v81, v81
	v_add_f32_e32 v168, v168, v80
	v_add_f32_e32 v168, v168, v81
	v_cvt_pk_bf16_f32 v80, v80, v81
	s_waitcnt lgkmcnt(6)
	v_mfma_f32_32x32x16_bf16 v[64:79], v[178:181], v[102:105], v[64:79]
	ds_read_b64_tr_b16 v[178:179], v96 offset:49152
	ds_read_b64_tr_b16 v[180:181], v96 offset:51200
	v_exp_f32_e32 v82, v82
	v_exp_f32_e32 v83, v83
	v_add_f32_e32 v168, v168, v82
	v_add_f32_e32 v168, v168, v83
	v_cvt_pk_bf16_f32 v81, v82, v83
	s_waitcnt lgkmcnt(7)
	v_mfma_f32_32x32x16_bf16 v[64:79], v[188:191], v[106:109], v[64:79]
	ds_read_b64_tr_b16 v[188:189], v132 offset:49152
	ds_read_b64_tr_b16 v[190:191], v132 offset:51200
	v_exp_f32_e32 v84, v84
	v_exp_f32_e32 v85, v85
	v_add_f32_e32 v168, v168, v84
	v_add_f32_e32 v168, v168, v85
	v_cvt_pk_bf16_f32 v82, v84, v85
	s_waitcnt lgkmcnt(8)
	v_mfma_f32_32x32x16_bf16 v[64:79], v[192:195], v[110:113], v[64:79]
	ds_read_b64_tr_b16 v[192:193], v134 offset:49152
	ds_read_b64_tr_b16 v[194:195], v134 offset:51200
	v_exp_f32_e32 v86, v86
	v_exp_f32_e32 v87, v87
	v_add_f32_e32 v168, v168, v86
	v_add_f32_e32 v168, v168, v87
	v_cvt_pk_bf16_f32 v83, v86, v87
	s_waitcnt lgkmcnt(9)
	v_mfma_f32_32x32x16_bf16 v[64:79], v[198:201], v[114:117], v[64:79]
	ds_read_b64_tr_b16 v[198:199], v135 offset:49152
	ds_read_b64_tr_b16 v[200:201], v135 offset:51200
	v_exp_f32_e32 v88, v88
	v_exp_f32_e32 v89, v89
	v_add_f32_e32 v168, v168, v88
	v_add_f32_e32 v168, v168, v89
	v_cvt_pk_bf16_f32 v84, v88, v89
	s_waitcnt lgkmcnt(10)
	v_mfma_f32_32x32x16_bf16 v[64:79], v[202:205], v[118:121], v[64:79]
	ds_read_b64_tr_b16 v[202:203], v96 offset:53248
	ds_read_b64_tr_b16 v[204:205], v96 offset:55296
	v_exp_f32_e32 v90, v90
	v_exp_f32_e32 v91, v91
	v_add_f32_e32 v168, v168, v90
	v_add_f32_e32 v168, v168, v91
	v_cvt_pk_bf16_f32 v85, v90, v91
	s_waitcnt lgkmcnt(11)
	v_mfma_f32_32x32x16_bf16 v[64:79], v[170:173], v[122:125], v[64:79]
	ds_read_b64_tr_b16 v[170:171], v132 offset:53248
	ds_read_b64_tr_b16 v[172:173], v132 offset:55296
	v_exp_f32_e32 v92, v92
	v_exp_f32_e32 v93, v93
	v_add_f32_e32 v168, v168, v92
	v_add_f32_e32 v168, v168, v93
	v_cvt_pk_bf16_f32 v86, v92, v93
	s_waitcnt lgkmcnt(12)
	v_mfma_f32_32x32x16_bf16 v[64:79], v[174:177], v[126:129], v[64:79]
	ds_read_b64_tr_b16 v[174:175], v134 offset:53248
	ds_read_b64_tr_b16 v[176:177], v134 offset:55296
	v_exp_f32_e32 v94, v94
	v_exp_f32_e32 v95, v95
	v_add_f32_e32 v168, v168, v94
	v_add_f32_e32 v168, v168, v95
	v_cvt_pk_bf16_f32 v87, v94, v95
	s_waitcnt lgkmcnt(12)
	v_mfma_f32_32x32x16_bf16 v[48:63], v[178:181], v[80:83], v[48:63]
	ds_read_b64_tr_b16 v[178:179], v135 offset:53248
	ds_read_b64_tr_b16 v[180:181], v135 offset:55296
	s_waitcnt lgkmcnt(12)
	v_mfma_f32_32x32x16_bf16 v[32:47], v[188:191], v[80:83], v[32:47]
	ds_read_b64_tr_b16 v[188:189], v96 offset:57344
	ds_read_b64_tr_b16 v[190:191], v96 offset:59392
	s_waitcnt lgkmcnt(12)
	v_mfma_f32_32x32x16_bf16 v[16:31], v[192:195], v[80:83], v[16:31]
	ds_read_b64_tr_b16 v[192:193], v132 offset:57344
	ds_read_b64_tr_b16 v[194:195], v132 offset:59392
	v_exp_f32_e32 v64, v64
	v_exp_f32_e32 v65, v65
	v_add_f32_e32 v168, v168, v64
	v_add_f32_e32 v168, v168, v65
	v_cvt_pk_bf16_f32 v88, v64, v65
	s_waitcnt lgkmcnt(12)
	v_mfma_f32_32x32x16_bf16 v[0:15], v[198:201], v[80:83], v[0:15]
	ds_read_b64_tr_b16 v[198:199], v134 offset:57344
	ds_read_b64_tr_b16 v[200:201], v134 offset:59392
	v_exp_f32_e32 v66, v66
	v_exp_f32_e32 v67, v67
	v_add_f32_e32 v168, v168, v66
	v_add_f32_e32 v168, v168, v67
	v_cvt_pk_bf16_f32 v89, v66, v67
	s_waitcnt lgkmcnt(12)
	v_mfma_f32_32x32x16_bf16 v[48:63], v[202:205], v[84:87], v[48:63]
	ds_read_b64_tr_b16 v[202:203], v135 offset:57344
	ds_read_b64_tr_b16 v[204:205], v135 offset:59392
	v_exp_f32_e32 v68, v68
	v_exp_f32_e32 v69, v69
	v_add_f32_e32 v168, v168, v68
	v_add_f32_e32 v168, v168, v69
	v_cvt_pk_bf16_f32 v90, v68, v69
	s_waitcnt lgkmcnt(12)
	v_mfma_f32_32x32x16_bf16 v[32:47], v[170:173], v[84:87], v[32:47]
	ds_read_b64_tr_b16 v[170:171], v96 offset:61440
	ds_read_b64_tr_b16 v[172:173], v96 offset:63488
	v_exp_f32_e32 v70, v70
	v_exp_f32_e32 v71, v71
	v_add_f32_e32 v168, v168, v70
	v_add_f32_e32 v168, v168, v71
	v_cvt_pk_bf16_f32 v91, v70, v71
	s_waitcnt lgkmcnt(12)
	v_mfma_f32_32x32x16_bf16 v[16:31], v[174:177], v[84:87], v[16:31]
	ds_read_b64_tr_b16 v[174:175], v132 offset:61440
	ds_read_b64_tr_b16 v[176:177], v132 offset:63488
	s_waitcnt lgkmcnt(12)
	v_mfma_f32_32x32x16_bf16 v[0:15], v[178:181], v[84:87], v[0:15]
	ds_read_b64_tr_b16 v[178:179], v134 offset:61440
	ds_read_b64_tr_b16 v[180:181], v134 offset:63488
	v_exp_f32_e32 v72, v72
	v_exp_f32_e32 v73, v73
	v_add_f32_e32 v168, v168, v72
	v_add_f32_e32 v168, v168, v73
	v_cvt_pk_bf16_f32 v92, v72, v73
	s_waitcnt lgkmcnt(12)
	v_mfma_f32_32x32x16_bf16 v[48:63], v[188:191], v[88:91], v[48:63]
	ds_read_b64_tr_b16 v[188:189], v135 offset:61440
	ds_read_b64_tr_b16 v[190:191], v135 offset:63488
	v_exp_f32_e32 v74, v74
	v_exp_f32_e32 v75, v75
	v_add_f32_e32 v168, v168, v74
	v_add_f32_e32 v168, v168, v75
	v_cvt_pk_bf16_f32 v93, v74, v75
	s_waitcnt lgkmcnt(12)
	v_mfma_f32_32x32x16_bf16 v[32:47], v[192:195], v[88:91], v[32:47]
	v_exp_f32_e32 v76, v76
	v_exp_f32_e32 v77, v77
	v_add_f32_e32 v168, v168, v76
	v_add_f32_e32 v168, v168, v77
	v_cvt_pk_bf16_f32 v94, v76, v77
	s_waitcnt lgkmcnt(10)
	v_mfma_f32_32x32x16_bf16 v[16:31], v[198:201], v[88:91], v[16:31]
	v_exp_f32_e32 v78, v78
	v_exp_f32_e32 v79, v79
	v_add_f32_e32 v168, v168, v78
	v_add_f32_e32 v168, v168, v79
	v_cvt_pk_bf16_f32 v95, v78, v79
	s_waitcnt lgkmcnt(8)
	v_mfma_f32_32x32x16_bf16 v[0:15], v[202:205], v[88:91], v[0:15]
	s_waitcnt lgkmcnt(6)
	v_mfma_f32_32x32x16_bf16 v[48:63], v[170:173], v[92:95], v[48:63]
	s_waitcnt lgkmcnt(4)
	v_mfma_f32_32x32x16_bf16 v[32:47], v[174:177], v[92:95], v[32:47]
	s_waitcnt lgkmcnt(2)
	v_mfma_f32_32x32x16_bf16 v[16:31], v[178:181], v[92:95], v[16:31]
	s_waitcnt lgkmcnt(0)
	v_mfma_f32_32x32x16_bf16 v[0:15], v[188:191], v[92:95], v[0:15]
	s_branch .LBB0_89
